# P1 sample tile: the two 64-byte halves of every 128-byte line requested back to back (were 8 loads apart) - L1 line-pair ordering
# baseline (speedup 1.0000x reference)
; #define LAS __attribute__((address_space(3)))
; #define SGT_LOAD(S_, KS_) do { _Pragma("unroll") for (int u = 0; u < U; ++u) { a0[S_][u] = *(const bf16x8*)(ap + (KS_) + 32 * u); if (MB == 2) a1[S_][u] = *(const bf16x8*)(ap + (size_t)16 * lda + (KS_) + 32 * u); \
;         _Pragma("unroll") for (int n = 0; n < NBW; ++n) b[S_][u][n] = *(const bf16x8*)(bp + (size_t)n * 16 * K + (KS_) + 32 * u); } } while (0)
; #define SGT_MMA(S_) do { _Pragma("unroll") for (int u = 0; u < U; ++u) _Pragma("unroll") for (int n = 0; n < NBW; ++n) { acc[0][n] = __builtin_amdgcn_mfma_f32_16x16x32_bf16(b[S_][u][n], a0[S_][u], acc[0][n], 0, 0, 0); \
;         if (MB == 2) acc[MB - 1][n] = __builtin_amdgcn_mfma_f32_16x16x32_bf16(b[S_][u][n], a1[S_][u], acc[MB - 1][n], 0, 0, 0); } } while (0)
;     ...
;     const bf16* ap = A + (size_t)(row0 + fr) * lda + k0 + 8 * fq;
;     const bf16* bp = Bt + (size_t)(col0 + wn * (TN / WN) + fr) * K + k0 + 8 * fq;
;     bf16x8 a0[2][U], a1[2][U], b[2][U][NBW];
;     ...
;     constexpr bool ONEPASS = 16 * MB * (TN / 4) <= NWAVES * 64;
;     typename F::Pre pre{};
;     if constexpr (ONEPASS) { if (tid < 16 * MB * (TN / 4)) pre = f.prefetch(tid / (TN / 4), 4 * (tid % (TN / 4))); }
;     SGT_LOAD(0, 0);
; #pragma unroll 1
;     for (int ks = 0; ks < KPER; ks += 64 * U) {
;         if (ks + 32 * U < KPER) SGT_LOAD(1, ks + 32 * U);
;         SGT_MMA(0);
;         if (ks + 64 * U < KPER) SGT_LOAD(0, ks + 64 * U);
;         if (ks + 32 * U < KPER) SGT_MMA(1);
;     }
;     ...
;     if constexpr (PREBAR) { asm volatile("s_waitcnt vmcnt(0)" ::: "memory"); __syncthreads(); }
;     LAS float* red = (LAS float*)lds;
; #pragma unroll
;     for (int m = 0; m < MB; ++m)
; #pragma unroll
;         for (int n = 0; n < NBW; ++n) *(LAS f32x4*)(red + (size_t)((wk * 16 * MB + 16 * m + fr) * P + wn * (TN / WN) + 16 * n + 4 * fq)) = acc[m][n];
;     __syncthreads();
.LBB0_567:
	s_lshl_b32 s0, s5, 1
	s_and_b32 s22, s0, 0xffffffe0
	s_and_b32 s0, s5, 15
	s_mul_i32 s17, s0, 0x60
	v_readfirstlane_b32 s0, v5
	s_addk_i32 s22, 0x4000
	s_ashr_i32 s16, s0, 6
	s_lshl_b32 s0, s16, 8
	v_or_b32_e32 v2, s17, v24
	v_lshlrev_b32_e32 v8, 11, v2
	v_add3_u32 v8, v8, s0, v6
	v_or_b32_e32 v2, s22, v24
	v_lshlrev_b32_e32 v9, 11, v2
	v_add3_u32 v9, v9, s0, v6
	s_mov_b64 s[68:69], s[8:9]
	s_add_u32 s70, s8, 0x8000
	s_addc_u32 s71, s9, 0
	s_add_u32 s72, s8, 0x10000
	s_addc_u32 s73, s9, 0
	s_add_u32 s74, s8, 0x18000
	s_addc_u32 s75, s9, 0
	s_add_u32 s76, s8, 0x20000
	s_addc_u32 s77, s9, 0
	s_add_u32 s78, s8, 0x28000
	s_addc_u32 s79, s9, 0
	s_mov_b64 s[80:81], s[10:11]
	s_add_u32 s82, s10, 0x8000
	s_addc_u32 s83, s11, 0
	global_load_dwordx4 v[28:31], v9, s[80:81]
	global_load_dwordx4 v[32:35], v9, s[80:81] offset:64
	global_load_dwordx4 v[44:47], v9, s[82:83]
	global_load_dwordx4 v[48:51], v9, s[82:83] offset:64
	global_load_dwordx4 v[10:13], v8, s[68:69]
	global_load_dwordx4 v[140:143], v8, s[68:69] offset:64
	global_load_dwordx4 v[14:17], v8, s[70:71]
	global_load_dwordx4 v[176:179], v8, s[70:71] offset:64
	global_load_dwordx4 v[18:21], v8, s[72:73]
	global_load_dwordx4 v[182:185], v8, s[72:73] offset:64
	global_load_dwordx4 v[128:131], v8, s[74:75]
	global_load_dwordx4 v[186:189], v8, s[74:75] offset:64
	global_load_dwordx4 v[132:135], v8, s[76:77]
	global_load_dwordx4 v[190:193], v8, s[76:77] offset:64
	global_load_dwordx4 v[136:139], v8, s[78:79]
	global_load_dwordx4 v[194:197], v8, s[78:79] offset:64
	global_load_dwordx4 v[36:39], v9, s[80:81] offset:128
	global_load_dwordx4 v[40:43], v9, s[80:81] offset:192
	global_load_dwordx4 v[52:55], v9, s[82:83] offset:128
	global_load_dwordx4 v[56:59], v9, s[82:83] offset:192
	global_load_dwordx4 v[198:201], v8, s[68:69] offset:128
	global_load_dwordx4 v[226:229], v8, s[68:69] offset:192
	global_load_dwordx4 v[202:205], v8, s[70:71] offset:128
	global_load_dwordx4 v[230:233], v8, s[70:71] offset:192
	global_load_dwordx4 v[206:209], v8, s[72:73] offset:128
	global_load_dwordx4 v[234:237], v8, s[72:73] offset:192
	global_load_dwordx4 v[214:217], v8, s[74:75] offset:128
	global_load_dwordx4 v[238:241], v8, s[74:75] offset:192
	global_load_dwordx4 v[218:221], v8, s[76:77] offset:128
	global_load_dwordx4 v[242:245], v8, s[76:77] offset:192
	global_load_dwordx4 v[222:225], v8, s[78:79] offset:128
	global_load_dwordx4 v[248:251], v8, s[78:79] offset:192
	v_lshl_or_b32 v2, s16, 5, v24
	s_movk_i32 s0, 0x190
	v_mad_u32_u24 v22, v2, s0, v4
	s_waitcnt vmcnt(17)
	v_mfma_f32_16x16x32_bf16 v[60:63], v[10:13], v[28:31], 0
	v_mfma_f32_16x16x32_bf16 v[84:87], v[10:13], v[44:47], 0
	v_mfma_f32_16x16x32_bf16 v[64:67], v[14:17], v[28:31], 0
	v_mfma_f32_16x16x32_bf16 v[108:111], v[14:17], v[44:47], 0
	v_mfma_f32_16x16x32_bf16 v[68:71], v[18:21], v[28:31], 0
	v_mfma_f32_16x16x32_bf16 v[112:115], v[18:21], v[44:47], 0
	v_mfma_f32_16x16x32_bf16 v[72:75], v[128:131], v[28:31], 0
	v_mfma_f32_16x16x32_bf16 v[116:119], v[128:131], v[44:47], 0
	v_mfma_f32_16x16x32_bf16 v[76:79], v[132:135], v[28:31], 0
	v_mfma_f32_16x16x32_bf16 v[120:123], v[132:135], v[44:47], 0
	v_mfma_f32_16x16x32_bf16 v[80:83], v[136:139], v[28:31], 0
	v_mfma_f32_16x16x32_bf16 v[124:127], v[136:139], v[44:47], 0
	s_waitcnt vmcnt(16)
	v_mfma_f32_16x16x32_bf16 v[60:63], v[140:143], v[32:35], v[60:63]
	v_mfma_f32_16x16x32_bf16 v[84:87], v[140:143], v[48:51], v[84:87]
	v_mfma_f32_16x16x32_bf16 v[64:67], v[176:179], v[32:35], v[64:67]
	v_mfma_f32_16x16x32_bf16 v[108:111], v[176:179], v[48:51], v[108:111]
	v_mfma_f32_16x16x32_bf16 v[68:71], v[182:185], v[32:35], v[68:71]
	v_mfma_f32_16x16x32_bf16 v[112:115], v[182:185], v[48:51], v[112:115]
	v_mfma_f32_16x16x32_bf16 v[72:75], v[186:189], v[32:35], v[72:75]
	v_mfma_f32_16x16x32_bf16 v[116:119], v[186:189], v[48:51], v[116:119]
	v_mfma_f32_16x16x32_bf16 v[76:79], v[190:193], v[32:35], v[76:79]
	v_mfma_f32_16x16x32_bf16 v[120:123], v[190:193], v[48:51], v[120:123]
	v_mfma_f32_16x16x32_bf16 v[80:83], v[194:197], v[32:35], v[80:83]
	v_mfma_f32_16x16x32_bf16 v[124:127], v[194:197], v[48:51], v[124:127]
	s_waitcnt vmcnt(1)
	v_mfma_f32_16x16x32_bf16 v[60:63], v[198:201], v[36:39], v[60:63]
	v_mfma_f32_16x16x32_bf16 v[84:87], v[198:201], v[52:55], v[84:87]
	v_mfma_f32_16x16x32_bf16 v[64:67], v[202:205], v[36:39], v[64:67]
	v_mfma_f32_16x16x32_bf16 v[108:111], v[202:205], v[52:55], v[108:111]
	v_mfma_f32_16x16x32_bf16 v[68:71], v[206:209], v[36:39], v[68:71]
	v_mfma_f32_16x16x32_bf16 v[112:115], v[206:209], v[52:55], v[112:115]
	v_mfma_f32_16x16x32_bf16 v[72:75], v[214:217], v[36:39], v[72:75]
	v_mfma_f32_16x16x32_bf16 v[116:119], v[214:217], v[52:55], v[116:119]
	v_mfma_f32_16x16x32_bf16 v[76:79], v[218:221], v[36:39], v[76:79]
	v_mfma_f32_16x16x32_bf16 v[120:123], v[218:221], v[52:55], v[120:123]
	v_mfma_f32_16x16x32_bf16 v[80:83], v[222:225], v[36:39], v[80:83]
	v_mfma_f32_16x16x32_bf16 v[124:127], v[222:225], v[52:55], v[124:127]
	s_waitcnt vmcnt(0)
	v_mfma_f32_16x16x32_bf16 v[60:63], v[226:229], v[40:43], v[60:63]
	v_mfma_f32_16x16x32_bf16 v[84:87], v[226:229], v[56:59], v[84:87]
	v_mfma_f32_16x16x32_bf16 v[64:67], v[230:233], v[40:43], v[64:67]
	v_mfma_f32_16x16x32_bf16 v[108:111], v[230:233], v[56:59], v[108:111]
	v_mfma_f32_16x16x32_bf16 v[68:71], v[234:237], v[40:43], v[68:71]
	v_mfma_f32_16x16x32_bf16 v[112:115], v[234:237], v[56:59], v[112:115]
	v_mfma_f32_16x16x32_bf16 v[72:75], v[238:241], v[40:43], v[72:75]
	v_mfma_f32_16x16x32_bf16 v[116:119], v[238:241], v[56:59], v[116:119]
	v_mfma_f32_16x16x32_bf16 v[76:79], v[242:245], v[40:43], v[76:79]
	v_mfma_f32_16x16x32_bf16 v[120:123], v[242:245], v[56:59], v[120:123]
	v_mfma_f32_16x16x32_bf16 v[80:83], v[248:251], v[40:43], v[80:83]
	v_mfma_f32_16x16x32_bf16 v[124:127], v[248:251], v[56:59], v[124:127]
	ds_write_b128 v22, v[60:63]
	ds_write_b128 v22, v[84:87] offset:6400
	ds_write_b128 v22, v[64:67] offset:64
	ds_write_b128 v22, v[108:111] offset:6464
	ds_write_b128 v22, v[68:71] offset:128
	ds_write_b128 v22, v[112:115] offset:6528
	ds_write_b128 v22, v[72:75] offset:192
	ds_write_b128 v22, v[116:119] offset:6592
	ds_write_b128 v22, v[76:79] offset:256
	ds_write_b128 v22, v[120:123] offset:6656
	ds_write_b128 v22, v[80:83] offset:320
	ds_write_b128 v22, v[124:127] offset:6720
	s_waitcnt lgkmcnt(0)
	s_barrier
	s_and_saveexec_b64 s[16:17], vcc
	s_cbranch_execz .LBB0_566
	s_and_b32 s23, s4, 15
	s_mulk_i32 s23, 0x60
	v_lshlrev_b32_e32 v7, 2, v5
	v_lshl_add_u32 v14, v5, 4, 0
	s_mov_b64 s[18:19], 0
	v_mov_b32_e32 v15, v5
	s_branch .LBB0_570
